# kind-11 gated-merge final epilogue: bf16 stores lane-transposed (permlane16_swap + ds_bpermute -> dwordx4, 64B per row per 4 lanes)
# baseline (speedup 1.0000x reference)
; __device__ __forceinline__ u32x2 pack4(f32x4 v) { u32x2 r; r[0] = cvt_pk(v[0], v[1]); r[1] = cvt_pk(v[2], v[3]); return r; }
; __device__ __forceinline__ f32x4 unpack4(u32x2 u) { f32x4 r; r[0] = bflo(u[0]); r[1] = bfhi(u[0]); r[2] = bflo(u[1]); r[3] = bfhi(u[1]); return r; }
; __device__ __forceinline__ void epilogue(const Params& p, const Unit& u, const f32x4 (&acc)[2][2][4][2], int wr, int wc, int fr, int fq) {
;     ...
;     for (int ai = 0; ai < 2; ++ai)
; #pragma unroll
;       for (int mp = 0; mp < 2; ++mp) {
;         u32x2 gr[2][2][2]; f32x4 mv[2][2][2];
; #pragma unroll
;         for (int mm = 0; mm < 2; ++mm)
; #pragma unroll
;           for (int bj = 0; bj < 2; ++bj)
; #pragma unroll
;             for (int n = 0; n < 2; ++n) {
;               const size_t row = (size_t)(row0 + ai * 128 + (mp * 2 + mm) * 16);
;               const int col = cb + bj * 128 + n * 16;
;               gr[mm][bj][n] = *(const u32x2*)(gates + row * 6144 + seg * 2048 + col);
;               if (seg > 0) mv[mm][bj][n] = *(const f32x4*)(mf + row * 2048 + col);
;             }
; #pragma unroll
;         for (int mm = 0; mm < 2; ++mm)
; #pragma unroll
;           for (int bj = 0; bj < 2; ++bj)
; #pragma unroll
;             for (int n = 0; n < 2; ++n) {
;               const size_t row = (size_t)(row0 + ai * 128 + (mp * 2 + mm) * 16);
;               const int col = cb + bj * 128 + n * 16;
;               f32x4 v = acc[ai][bj][mp * 2 + mm][n] * unpack4(gr[mm][bj][n]);
;               if (seg > 0) v += mv[mm][bj][n];
;               if (seg < 2) *(f32x4*)(mf + row * 2048 + col) = v;
;               else *(u32x2*)(mb + row * 2048 + col) = pack4(v);
;             }
.Lgm_fin:
	s_add_u32 s38, s24, 0x17b09000
	s_addc_u32 s39, s25, 0
	global_load_dwordx2 v[132:133], v64, s[34:35] offset:0
	global_load_dwordx2 v[134:135], v64, s[34:35] offset:32
	global_load_dwordx2 v[136:137], v64, s[34:35] offset:256
	global_load_dwordx2 v[138:139], v64, s[34:35] offset:288
	v_add_u32_e32 v64, 0x30000, v64
	global_load_dwordx2 v[140:141], v64, s[34:35] offset:0
	global_load_dwordx2 v[142:143], v64, s[34:35] offset:32
	global_load_dwordx2 v[144:145], v64, s[34:35] offset:256
	global_load_dwordx2 v[146:147], v64, s[34:35] offset:288
	v_add_u32_e32 v64, 0x30000, v64
	global_load_dwordx2 v[148:149], v64, s[34:35] offset:0
	global_load_dwordx2 v[150:151], v64, s[34:35] offset:32
	global_load_dwordx2 v[152:153], v64, s[34:35] offset:256
	global_load_dwordx2 v[154:155], v64, s[34:35] offset:288
	v_add_u32_e32 v64, 0x30000, v64
	global_load_dwordx2 v[156:157], v64, s[34:35] offset:0
	global_load_dwordx2 v[158:159], v64, s[34:35] offset:32
	global_load_dwordx2 v[160:161], v64, s[34:35] offset:256
	global_load_dwordx2 v[162:163], v64, s[34:35] offset:288
	v_add_u32_e32 v64, 0xf0000, v64
	global_load_dwordx2 v[164:165], v64, s[34:35] offset:0
	global_load_dwordx2 v[166:167], v64, s[34:35] offset:32
	global_load_dwordx2 v[196:197], v64, s[34:35] offset:256
	global_load_dwordx2 v[198:199], v64, s[34:35] offset:288
	v_add_u32_e32 v64, 0x30000, v64
	global_load_dwordx2 v[200:201], v64, s[34:35] offset:0
	global_load_dwordx2 v[202:203], v64, s[34:35] offset:32
	global_load_dwordx2 v[204:205], v64, s[34:35] offset:256
	global_load_dwordx2 v[206:207], v64, s[34:35] offset:288
	v_add_u32_e32 v64, 0x30000, v64
	global_load_dwordx2 v[208:209], v64, s[34:35] offset:0
	global_load_dwordx2 v[210:211], v64, s[34:35] offset:32
	global_load_dwordx2 v[212:213], v64, s[34:35] offset:256
	global_load_dwordx2 v[214:215], v64, s[34:35] offset:288
	v_add_u32_e32 v64, 0x30000, v64
	global_load_dwordx2 v[216:217], v64, s[34:35] offset:0
	global_load_dwordx2 v[218:219], v64, s[34:35] offset:32
	global_load_dwordx2 v[220:221], v64, s[34:35] offset:256
	global_load_dwordx2 v[222:223], v64, s[34:35] offset:288
	v_lshrrev_b32_e32 v245, 2, v230
	v_and_b32_e32 v246, 3, v230
	v_lshlrev_b32_e32 v247, 1, v246
	v_lshrrev_b32_e32 v244, 1, v246
	v_or_b32_e32 v244, v247, v244
	v_and_b32_e32 v244, 3, v244
	v_lshlrev_b32_e32 v244, 6, v244
	v_lshl_add_u32 v244, v245, 2, v244
	v_and_b32_e32 v247, 15, v169
	v_sub_u32_e32 v247, v66, v247
	v_add_u32_e32 v247, v247, v245
	v_and_b32_e32 v67, 0x60, v174
	v_lshl_or_b32 v67, s78, 8, v67
	v_lshlrev_b32_e32 v67, 1, v67
	v_lshl_add_u32 v67, v246, 4, v67
	v_lshl_add_u32 v67, v247, 12, v67
	s_waitcnt vmcnt(31)
	v_lshlrev_b32_e32 v232, 16, v132
	v_and_b32_e32 v233, s30, v132
	v_lshlrev_b32_e32 v234, 16, v133
	v_and_b32_e32 v235, s30, v133
	v_max_f32_e32 v232, s31, v232
	v_max_f32_e32 v233, s31, v233
	v_max_f32_e32 v234, s31, v234
	v_max_f32_e32 v235, s31, v235
	v_pk_mul_f32 v[128:129], v[128:129], v[232:233]
	v_pk_mul_f32 v[130:131], v[130:131], v[234:235]
	v_cvt_pk_bf16_f32 v132, v128, v129
	v_cvt_pk_bf16_f32 v133, v130, v131
	s_waitcnt vmcnt(30)
	v_lshlrev_b32_e32 v232, 16, v134
	v_and_b32_e32 v233, s30, v134
	v_lshlrev_b32_e32 v234, 16, v135
	v_and_b32_e32 v235, s30, v135
	v_max_f32_e32 v232, s31, v232
	v_max_f32_e32 v233, s31, v233
	v_max_f32_e32 v234, s31, v234
	v_max_f32_e32 v235, s31, v235
	v_pk_mul_f32 v[124:125], v[124:125], v[232:233]
	v_pk_mul_f32 v[126:127], v[126:127], v[234:235]
	v_cvt_pk_bf16_f32 v134, v124, v125
	v_cvt_pk_bf16_f32 v135, v126, v127
	s_nop 1
	v_permlane16_swap_b32_e32 v132, v134
	v_permlane16_swap_b32_e32 v133, v135
	ds_bpermute_b32 v132, v244, v132
	ds_bpermute_b32 v133, v244, v133
	ds_bpermute_b32 v134, v244, v134
	ds_bpermute_b32 v135, v244, v135
	s_waitcnt vmcnt(29)
	v_lshlrev_b32_e32 v232, 16, v136
	v_and_b32_e32 v233, s30, v136
	v_lshlrev_b32_e32 v234, 16, v137
	v_and_b32_e32 v235, s30, v137
	v_max_f32_e32 v232, s31, v232
	v_max_f32_e32 v233, s31, v233
	v_max_f32_e32 v234, s31, v234
	v_max_f32_e32 v235, s31, v235
	v_pk_mul_f32 v[96:97], v[96:97], v[232:233]
	v_pk_mul_f32 v[98:99], v[98:99], v[234:235]
	v_cvt_pk_bf16_f32 v136, v96, v97
	v_cvt_pk_bf16_f32 v137, v98, v99
	s_waitcnt vmcnt(28)
	v_lshlrev_b32_e32 v232, 16, v138
	v_and_b32_e32 v233, s30, v138
	v_lshlrev_b32_e32 v234, 16, v139
	v_and_b32_e32 v235, s30, v139
	v_max_f32_e32 v232, s31, v232
	v_max_f32_e32 v233, s31, v233
	v_max_f32_e32 v234, s31, v234
	v_max_f32_e32 v235, s31, v235
	v_pk_mul_f32 v[92:93], v[92:93], v[232:233]
	v_pk_mul_f32 v[94:95], v[94:95], v[234:235]
	v_cvt_pk_bf16_f32 v138, v92, v93
	v_cvt_pk_bf16_f32 v139, v94, v95
	s_nop 1
	v_permlane16_swap_b32_e32 v136, v138
	v_permlane16_swap_b32_e32 v137, v139
	ds_bpermute_b32 v136, v244, v136
	ds_bpermute_b32 v137, v244, v137
	ds_bpermute_b32 v138, v244, v138
	ds_bpermute_b32 v139, v244, v139
	s_waitcnt lgkmcnt(4)
	global_store_dwordx4 v67, v[132:135], s[38:39] offset:0
	s_waitcnt vmcnt(28)
	v_lshlrev_b32_e32 v232, 16, v140
	v_and_b32_e32 v233, s30, v140
	v_lshlrev_b32_e32 v234, 16, v141
	v_and_b32_e32 v235, s30, v141
	v_max_f32_e32 v232, s31, v232
	v_max_f32_e32 v233, s31, v233
	v_max_f32_e32 v234, s31, v234
	v_max_f32_e32 v235, s31, v235
	v_pk_mul_f32 v[120:121], v[120:121], v[232:233]
	v_pk_mul_f32 v[122:123], v[122:123], v[234:235]
	v_cvt_pk_bf16_f32 v140, v120, v121
	v_cvt_pk_bf16_f32 v141, v122, v123
	s_waitcnt vmcnt(27)
; __device__ __forceinline__ u32x2 pack4(f32x4 v) { u32x2 r; r[0] = cvt_pk(v[0], v[1]); r[1] = cvt_pk(v[2], v[3]); return r; }
; __device__ __forceinline__ f32x4 unpack4(u32x2 u) { f32x4 r; r[0] = bflo(u[0]); r[1] = bfhi(u[0]); r[2] = bflo(u[1]); r[3] = bfhi(u[1]); return r; }
; __device__ __forceinline__ void epilogue(const Params& p, const Unit& u, const f32x4 (&acc)[2][2][4][2], int wr, int wc, int fr, int fq) {
;     ...
;     for (int ai = 0; ai < 2; ++ai)
; #pragma unroll
;       for (int mp = 0; mp < 2; ++mp) {
;         u32x2 gr[2][2][2]; f32x4 mv[2][2][2];
; #pragma unroll
;         for (int mm = 0; mm < 2; ++mm)
; #pragma unroll
;           for (int bj = 0; bj < 2; ++bj)
; #pragma unroll
;             for (int n = 0; n < 2; ++n) {
;               const size_t row = (size_t)(row0 + ai * 128 + (mp * 2 + mm) * 16);
;               const int col = cb + bj * 128 + n * 16;
;               gr[mm][bj][n] = *(const u32x2*)(gates + row * 6144 + seg * 2048 + col);
;               if (seg > 0) mv[mm][bj][n] = *(const f32x4*)(mf + row * 2048 + col);
;             }
; #pragma unroll
;         for (int mm = 0; mm < 2; ++mm)
; #pragma unroll
;           for (int bj = 0; bj < 2; ++bj)
; #pragma unroll
;             for (int n = 0; n < 2; ++n) {
;               const size_t row = (size_t)(row0 + ai * 128 + (mp * 2 + mm) * 16);
;               const int col = cb + bj * 128 + n * 16;
;               f32x4 v = acc[ai][bj][mp * 2 + mm][n] * unpack4(gr[mm][bj][n]);
;               if (seg > 0) v += mv[mm][bj][n];
;               if (seg < 2) *(f32x4*)(mf + row * 2048 + col) = v;
;               else *(u32x2*)(mb + row * 2048 + col) = pack4(v);
;             }
	v_lshlrev_b32_e32 v232, 16, v142
	v_and_b32_e32 v233, s30, v142
	v_lshlrev_b32_e32 v234, 16, v143
	v_and_b32_e32 v235, s30, v143
	v_max_f32_e32 v232, s31, v232
	v_max_f32_e32 v233, s31, v233
	v_max_f32_e32 v234, s31, v234
	v_max_f32_e32 v235, s31, v235
	v_pk_mul_f32 v[116:117], v[116:117], v[232:233]
	v_pk_mul_f32 v[118:119], v[118:119], v[234:235]
	v_cvt_pk_bf16_f32 v142, v116, v117
	v_cvt_pk_bf16_f32 v143, v118, v119
	s_nop 1
	v_permlane16_swap_b32_e32 v140, v142
	v_permlane16_swap_b32_e32 v141, v143
	ds_bpermute_b32 v140, v244, v140
	ds_bpermute_b32 v141, v244, v141
	ds_bpermute_b32 v142, v244, v142
	ds_bpermute_b32 v143, v244, v143
	s_waitcnt lgkmcnt(4)
	global_store_dwordx4 v67, v[136:139], s[38:39] offset:256
	v_add_u32_e32 v67, 0x10000, v67
	s_waitcnt vmcnt(27)
	v_lshlrev_b32_e32 v232, 16, v144
	v_and_b32_e32 v233, s30, v144
	v_lshlrev_b32_e32 v234, 16, v145
	v_and_b32_e32 v235, s30, v145
	v_max_f32_e32 v232, s31, v232
	v_max_f32_e32 v233, s31, v233
	v_max_f32_e32 v234, s31, v234
	v_max_f32_e32 v235, s31, v235
	v_pk_mul_f32 v[88:89], v[88:89], v[232:233]
	v_pk_mul_f32 v[90:91], v[90:91], v[234:235]
	v_cvt_pk_bf16_f32 v144, v88, v89
	v_cvt_pk_bf16_f32 v145, v90, v91
	s_waitcnt vmcnt(26)
	v_lshlrev_b32_e32 v232, 16, v146
	v_and_b32_e32 v233, s30, v146
	v_lshlrev_b32_e32 v234, 16, v147
	v_and_b32_e32 v235, s30, v147
	v_max_f32_e32 v232, s31, v232
	v_max_f32_e32 v233, s31, v233
	v_max_f32_e32 v234, s31, v234
	v_max_f32_e32 v235, s31, v235
	v_pk_mul_f32 v[84:85], v[84:85], v[232:233]
	v_pk_mul_f32 v[86:87], v[86:87], v[234:235]
	v_cvt_pk_bf16_f32 v146, v84, v85
	v_cvt_pk_bf16_f32 v147, v86, v87
	s_nop 1
	v_permlane16_swap_b32_e32 v144, v146
	v_permlane16_swap_b32_e32 v145, v147
	ds_bpermute_b32 v144, v244, v144
	ds_bpermute_b32 v145, v244, v145
	ds_bpermute_b32 v146, v244, v146
	ds_bpermute_b32 v147, v244, v147
	s_waitcnt lgkmcnt(4)
	global_store_dwordx4 v67, v[140:143], s[38:39] offset:0
	s_waitcnt vmcnt(26)
	v_lshlrev_b32_e32 v232, 16, v148
	v_and_b32_e32 v233, s30, v148
	v_lshlrev_b32_e32 v234, 16, v149
	v_and_b32_e32 v235, s30, v149
	v_max_f32_e32 v232, s31, v232
	v_max_f32_e32 v233, s31, v233
	v_max_f32_e32 v234, s31, v234
	v_max_f32_e32 v235, s31, v235
	v_pk_mul_f32 v[112:113], v[112:113], v[232:233]
	v_pk_mul_f32 v[114:115], v[114:115], v[234:235]
	v_cvt_pk_bf16_f32 v148, v112, v113
	v_cvt_pk_bf16_f32 v149, v114, v115
	s_waitcnt vmcnt(25)
	v_lshlrev_b32_e32 v232, 16, v150
	v_and_b32_e32 v233, s30, v150
	v_lshlrev_b32_e32 v234, 16, v151
	v_and_b32_e32 v235, s30, v151
	v_max_f32_e32 v232, s31, v232
	v_max_f32_e32 v233, s31, v233
	v_max_f32_e32 v234, s31, v234
	v_max_f32_e32 v235, s31, v235
	v_pk_mul_f32 v[108:109], v[108:109], v[232:233]
	v_pk_mul_f32 v[110:111], v[110:111], v[234:235]
	v_cvt_pk_bf16_f32 v150, v108, v109
	v_cvt_pk_bf16_f32 v151, v110, v111
	s_nop 1
	v_permlane16_swap_b32_e32 v148, v150
	v_permlane16_swap_b32_e32 v149, v151
	ds_bpermute_b32 v148, v244, v148
	ds_bpermute_b32 v149, v244, v149
	ds_bpermute_b32 v150, v244, v150
	ds_bpermute_b32 v151, v244, v151
	s_waitcnt lgkmcnt(4)
	global_store_dwordx4 v67, v[144:147], s[38:39] offset:256
	v_add_u32_e32 v67, 0x10000, v67
	s_waitcnt vmcnt(25)
	v_lshlrev_b32_e32 v232, 16, v152
	v_and_b32_e32 v233, s30, v152
	v_lshlrev_b32_e32 v234, 16, v153
	v_and_b32_e32 v235, s30, v153
	v_max_f32_e32 v232, s31, v232
	v_max_f32_e32 v233, s31, v233
	v_max_f32_e32 v234, s31, v234
	v_max_f32_e32 v235, s31, v235
	v_pk_mul_f32 v[80:81], v[80:81], v[232:233]
	v_pk_mul_f32 v[82:83], v[82:83], v[234:235]
	v_cvt_pk_bf16_f32 v152, v80, v81
	v_cvt_pk_bf16_f32 v153, v82, v83
	s_waitcnt vmcnt(24)
	v_lshlrev_b32_e32 v232, 16, v154
	v_and_b32_e32 v233, s30, v154
	v_lshlrev_b32_e32 v234, 16, v155
	v_and_b32_e32 v235, s30, v155
	v_max_f32_e32 v232, s31, v232
	v_max_f32_e32 v233, s31, v233
	v_max_f32_e32 v234, s31, v234
	v_max_f32_e32 v235, s31, v235
	v_pk_mul_f32 v[76:77], v[76:77], v[232:233]
	v_pk_mul_f32 v[78:79], v[78:79], v[234:235]
	v_cvt_pk_bf16_f32 v154, v76, v77
	v_cvt_pk_bf16_f32 v155, v78, v79
	s_nop 1
	v_permlane16_swap_b32_e32 v152, v154
	v_permlane16_swap_b32_e32 v153, v155
	ds_bpermute_b32 v152, v244, v152
	ds_bpermute_b32 v153, v244, v153
	ds_bpermute_b32 v154, v244, v154
	ds_bpermute_b32 v155, v244, v155
	s_waitcnt lgkmcnt(4)
	global_store_dwordx4 v67, v[148:151], s[38:39] offset:0
	s_waitcnt vmcnt(24)
	v_lshlrev_b32_e32 v232, 16, v156
	v_and_b32_e32 v233, s30, v156
	v_lshlrev_b32_e32 v234, 16, v157
	v_and_b32_e32 v235, s30, v157
	v_max_f32_e32 v232, s31, v232
	v_max_f32_e32 v233, s31, v233
	v_max_f32_e32 v234, s31, v234
	v_max_f32_e32 v235, s31, v235
	v_pk_mul_f32 v[104:105], v[104:105], v[232:233]
	v_pk_mul_f32 v[106:107], v[106:107], v[234:235]
	v_cvt_pk_bf16_f32 v156, v104, v105
	v_cvt_pk_bf16_f32 v157, v106, v107
	s_waitcnt vmcnt(23)
	v_lshlrev_b32_e32 v232, 16, v158
	v_and_b32_e32 v233, s30, v158
	v_lshlrev_b32_e32 v234, 16, v159
	v_and_b32_e32 v235, s30, v159
	v_max_f32_e32 v232, s31, v232
	v_max_f32_e32 v233, s31, v233
	v_max_f32_e32 v234, s31, v234
	v_max_f32_e32 v235, s31, v235
	v_pk_mul_f32 v[100:101], v[100:101], v[232:233]
	v_pk_mul_f32 v[102:103], v[102:103], v[234:235]
	v_cvt_pk_bf16_f32 v158, v100, v101
	v_cvt_pk_bf16_f32 v159, v102, v103
	s_nop 1
	v_permlane16_swap_b32_e32 v156, v158
	v_permlane16_swap_b32_e32 v157, v159
	ds_bpermute_b32 v156, v244, v156
	ds_bpermute_b32 v157, v244, v157
	ds_bpermute_b32 v158, v244, v158
	ds_bpermute_b32 v159, v244, v159
	s_waitcnt lgkmcnt(4)
	global_store_dwordx4 v67, v[152:155], s[38:39] offset:256
	v_add_u32_e32 v67, 0x10000, v67
	s_waitcnt vmcnt(23)
; __device__ __forceinline__ u32x2 pack4(f32x4 v) { u32x2 r; r[0] = cvt_pk(v[0], v[1]); r[1] = cvt_pk(v[2], v[3]); return r; }
; __device__ __forceinline__ f32x4 unpack4(u32x2 u) { f32x4 r; r[0] = bflo(u[0]); r[1] = bfhi(u[0]); r[2] = bflo(u[1]); r[3] = bfhi(u[1]); return r; }
; __device__ __forceinline__ void epilogue(const Params& p, const Unit& u, const f32x4 (&acc)[2][2][4][2], int wr, int wc, int fr, int fq) {
;     ...
; #pragma unroll
;         for (int mm = 0; mm < 2; ++mm)
; #pragma unroll
;           for (int bj = 0; bj < 2; ++bj)
; #pragma unroll
;             for (int n = 0; n < 2; ++n) {
;               const size_t row = (size_t)(row0 + ai * 128 + (mp * 2 + mm) * 16);
;               const int col = cb + bj * 128 + n * 16;
;               f32x4 v = acc[ai][bj][mp * 2 + mm][n] * unpack4(gr[mm][bj][n]);
;               if (seg > 0) v += mv[mm][bj][n];
;               if (seg < 2) *(f32x4*)(mf + row * 2048 + col) = v;
;               else *(u32x2*)(mb + row * 2048 + col) = pack4(v);
;             }
	v_lshlrev_b32_e32 v232, 16, v160
	v_and_b32_e32 v233, s30, v160
	v_lshlrev_b32_e32 v234, 16, v161
	v_and_b32_e32 v235, s30, v161
	v_max_f32_e32 v232, s31, v232
	v_max_f32_e32 v233, s31, v233
	v_max_f32_e32 v234, s31, v234
	v_max_f32_e32 v235, s31, v235
	v_pk_mul_f32 v[72:73], v[72:73], v[232:233]
	v_pk_mul_f32 v[74:75], v[74:75], v[234:235]
	v_cvt_pk_bf16_f32 v160, v72, v73
	v_cvt_pk_bf16_f32 v161, v74, v75
	s_waitcnt vmcnt(22)
	v_lshlrev_b32_e32 v232, 16, v162
	v_and_b32_e32 v233, s30, v162
	v_lshlrev_b32_e32 v234, 16, v163
	v_and_b32_e32 v235, s30, v163
	v_max_f32_e32 v232, s31, v232
	v_max_f32_e32 v233, s31, v233
	v_max_f32_e32 v234, s31, v234
	v_max_f32_e32 v235, s31, v235
	v_pk_mul_f32 v[68:69], v[68:69], v[232:233]
	v_pk_mul_f32 v[70:71], v[70:71], v[234:235]
	v_cvt_pk_bf16_f32 v162, v68, v69
	v_cvt_pk_bf16_f32 v163, v70, v71
	s_nop 1
	v_permlane16_swap_b32_e32 v160, v162
	v_permlane16_swap_b32_e32 v161, v163
	ds_bpermute_b32 v160, v244, v160
	ds_bpermute_b32 v161, v244, v161
	ds_bpermute_b32 v162, v244, v162
	ds_bpermute_b32 v163, v244, v163
	s_waitcnt lgkmcnt(4)
	global_store_dwordx4 v67, v[156:159], s[38:39] offset:0
	s_waitcnt vmcnt(22)
	v_lshlrev_b32_e32 v232, 16, v164
	v_and_b32_e32 v233, s30, v164
	v_lshlrev_b32_e32 v234, 16, v165
	v_and_b32_e32 v235, s30, v165
	v_max_f32_e32 v232, s31, v232
	v_max_f32_e32 v233, s31, v233
	v_max_f32_e32 v234, s31, v234
	v_max_f32_e32 v235, s31, v235
	v_pk_mul_f32 v[60:61], v[60:61], v[232:233]
	v_pk_mul_f32 v[62:63], v[62:63], v[234:235]
	v_cvt_pk_bf16_f32 v164, v60, v61
	v_cvt_pk_bf16_f32 v165, v62, v63
	s_waitcnt vmcnt(21)
	v_lshlrev_b32_e32 v232, 16, v166
	v_and_b32_e32 v233, s30, v166
	v_lshlrev_b32_e32 v234, 16, v167
	v_and_b32_e32 v235, s30, v167
	v_max_f32_e32 v232, s31, v232
	v_max_f32_e32 v233, s31, v233
	v_max_f32_e32 v234, s31, v234
	v_max_f32_e32 v235, s31, v235
	v_pk_mul_f32 v[56:57], v[56:57], v[232:233]
	v_pk_mul_f32 v[58:59], v[58:59], v[234:235]
	v_cvt_pk_bf16_f32 v166, v56, v57
	v_cvt_pk_bf16_f32 v167, v58, v59
	s_nop 1
	v_permlane16_swap_b32_e32 v164, v166
	v_permlane16_swap_b32_e32 v165, v167
	ds_bpermute_b32 v164, v244, v164
	ds_bpermute_b32 v165, v244, v165
	ds_bpermute_b32 v166, v244, v166
	ds_bpermute_b32 v167, v244, v167
	s_waitcnt lgkmcnt(4)
	global_store_dwordx4 v67, v[160:163], s[38:39] offset:256
	v_add_u32_e32 v67, 0x50000, v67
	s_waitcnt vmcnt(21)
	v_lshlrev_b32_e32 v232, 16, v196
	v_and_b32_e32 v233, s30, v196
	v_lshlrev_b32_e32 v234, 16, v197
	v_and_b32_e32 v235, s30, v197
	v_max_f32_e32 v232, s31, v232
	v_max_f32_e32 v233, s31, v233
	v_max_f32_e32 v234, s31, v234
	v_max_f32_e32 v235, s31, v235
	v_pk_mul_f32 v[28:29], v[28:29], v[232:233]
	v_pk_mul_f32 v[30:31], v[30:31], v[234:235]
	v_cvt_pk_bf16_f32 v196, v28, v29
	v_cvt_pk_bf16_f32 v197, v30, v31
	s_waitcnt vmcnt(20)
	v_lshlrev_b32_e32 v232, 16, v198
	v_and_b32_e32 v233, s30, v198
	v_lshlrev_b32_e32 v234, 16, v199
	v_and_b32_e32 v235, s30, v199
	v_max_f32_e32 v232, s31, v232
	v_max_f32_e32 v233, s31, v233
	v_max_f32_e32 v234, s31, v234
	v_max_f32_e32 v235, s31, v235
	v_pk_mul_f32 v[24:25], v[24:25], v[232:233]
	v_pk_mul_f32 v[26:27], v[26:27], v[234:235]
	v_cvt_pk_bf16_f32 v198, v24, v25
	v_cvt_pk_bf16_f32 v199, v26, v27
	s_nop 1
	v_permlane16_swap_b32_e32 v196, v198
	v_permlane16_swap_b32_e32 v197, v199
	ds_bpermute_b32 v196, v244, v196
	ds_bpermute_b32 v197, v244, v197
	ds_bpermute_b32 v198, v244, v198
	ds_bpermute_b32 v199, v244, v199
	s_waitcnt lgkmcnt(4)
	global_store_dwordx4 v67, v[164:167], s[38:39] offset:0
	s_waitcnt vmcnt(20)
	v_lshlrev_b32_e32 v232, 16, v200
	v_and_b32_e32 v233, s30, v200
	v_lshlrev_b32_e32 v234, 16, v201
	v_and_b32_e32 v235, s30, v201
	v_max_f32_e32 v232, s31, v232
	v_max_f32_e32 v233, s31, v233
	v_max_f32_e32 v234, s31, v234
	v_max_f32_e32 v235, s31, v235
	v_pk_mul_f32 v[52:53], v[52:53], v[232:233]
	v_pk_mul_f32 v[54:55], v[54:55], v[234:235]
	v_cvt_pk_bf16_f32 v200, v52, v53
	v_cvt_pk_bf16_f32 v201, v54, v55
	s_waitcnt vmcnt(19)
	v_lshlrev_b32_e32 v232, 16, v202
	v_and_b32_e32 v233, s30, v202
	v_lshlrev_b32_e32 v234, 16, v203
	v_and_b32_e32 v235, s30, v203
	v_max_f32_e32 v232, s31, v232
	v_max_f32_e32 v233, s31, v233
	v_max_f32_e32 v234, s31, v234
	v_max_f32_e32 v235, s31, v235
	v_pk_mul_f32 v[48:49], v[48:49], v[232:233]
	v_pk_mul_f32 v[50:51], v[50:51], v[234:235]
	v_cvt_pk_bf16_f32 v202, v48, v49
	v_cvt_pk_bf16_f32 v203, v50, v51
	s_nop 1
	v_permlane16_swap_b32_e32 v200, v202
	v_permlane16_swap_b32_e32 v201, v203
	ds_bpermute_b32 v200, v244, v200
	ds_bpermute_b32 v201, v244, v201
	ds_bpermute_b32 v202, v244, v202
	ds_bpermute_b32 v203, v244, v203
	s_waitcnt lgkmcnt(4)
	global_store_dwordx4 v67, v[196:199], s[38:39] offset:256
	v_add_u32_e32 v67, 0x10000, v67
	s_waitcnt vmcnt(19)
	v_lshlrev_b32_e32 v232, 16, v204
	v_and_b32_e32 v233, s30, v204
	v_lshlrev_b32_e32 v234, 16, v205
	v_and_b32_e32 v235, s30, v205
	v_max_f32_e32 v232, s31, v232
	v_max_f32_e32 v233, s31, v233
	v_max_f32_e32 v234, s31, v234
	v_max_f32_e32 v235, s31, v235
	v_pk_mul_f32 v[20:21], v[20:21], v[232:233]
	v_pk_mul_f32 v[22:23], v[22:23], v[234:235]
	v_cvt_pk_bf16_f32 v204, v20, v21
	v_cvt_pk_bf16_f32 v205, v22, v23
	s_waitcnt vmcnt(18)
; __device__ __forceinline__ u32x2 pack4(f32x4 v) { u32x2 r; r[0] = cvt_pk(v[0], v[1]); r[1] = cvt_pk(v[2], v[3]); return r; }
; __device__ __forceinline__ f32x4 unpack4(u32x2 u) { f32x4 r; r[0] = bflo(u[0]); r[1] = bfhi(u[0]); r[2] = bflo(u[1]); r[3] = bfhi(u[1]); return r; }
; __device__ __forceinline__ void epilogue(const Params& p, const Unit& u, const f32x4 (&acc)[2][2][4][2], int wr, int wc, int fr, int fq) {
;     ...
; #pragma unroll
;         for (int mm = 0; mm < 2; ++mm)
; #pragma unroll
;           for (int bj = 0; bj < 2; ++bj)
; #pragma unroll
;             for (int n = 0; n < 2; ++n) {
;               const size_t row = (size_t)(row0 + ai * 128 + (mp * 2 + mm) * 16);
;               const int col = cb + bj * 128 + n * 16;
;               f32x4 v = acc[ai][bj][mp * 2 + mm][n] * unpack4(gr[mm][bj][n]);
;               if (seg > 0) v += mv[mm][bj][n];
;               if (seg < 2) *(f32x4*)(mf + row * 2048 + col) = v;
;               else *(u32x2*)(mb + row * 2048 + col) = pack4(v);
;             }
	v_lshlrev_b32_e32 v232, 16, v206
	v_and_b32_e32 v233, s30, v206
	v_lshlrev_b32_e32 v234, 16, v207
	v_and_b32_e32 v235, s30, v207
	v_max_f32_e32 v232, s31, v232
	v_max_f32_e32 v233, s31, v233
	v_max_f32_e32 v234, s31, v234
	v_max_f32_e32 v235, s31, v235
	v_pk_mul_f32 v[16:17], v[16:17], v[232:233]
	v_pk_mul_f32 v[18:19], v[18:19], v[234:235]
	v_cvt_pk_bf16_f32 v206, v16, v17
	v_cvt_pk_bf16_f32 v207, v18, v19
	s_nop 1
	v_permlane16_swap_b32_e32 v204, v206
	v_permlane16_swap_b32_e32 v205, v207
	ds_bpermute_b32 v204, v244, v204
	ds_bpermute_b32 v205, v244, v205
	ds_bpermute_b32 v206, v244, v206
	ds_bpermute_b32 v207, v244, v207
	s_waitcnt lgkmcnt(4)
	global_store_dwordx4 v67, v[200:203], s[38:39] offset:0
	s_waitcnt vmcnt(18)
	v_lshlrev_b32_e32 v232, 16, v208
	v_and_b32_e32 v233, s30, v208
	v_lshlrev_b32_e32 v234, 16, v209
	v_and_b32_e32 v235, s30, v209
	v_max_f32_e32 v232, s31, v232
	v_max_f32_e32 v233, s31, v233
	v_max_f32_e32 v234, s31, v234
	v_max_f32_e32 v235, s31, v235
	v_pk_mul_f32 v[44:45], v[44:45], v[232:233]
	v_pk_mul_f32 v[46:47], v[46:47], v[234:235]
	v_cvt_pk_bf16_f32 v208, v44, v45
	v_cvt_pk_bf16_f32 v209, v46, v47
	s_waitcnt vmcnt(17)
	v_lshlrev_b32_e32 v232, 16, v210
	v_and_b32_e32 v233, s30, v210
	v_lshlrev_b32_e32 v234, 16, v211
	v_and_b32_e32 v235, s30, v211
	v_max_f32_e32 v232, s31, v232
	v_max_f32_e32 v233, s31, v233
	v_max_f32_e32 v234, s31, v234
	v_max_f32_e32 v235, s31, v235
	v_pk_mul_f32 v[40:41], v[40:41], v[232:233]
	v_pk_mul_f32 v[42:43], v[42:43], v[234:235]
	v_cvt_pk_bf16_f32 v210, v40, v41
	v_cvt_pk_bf16_f32 v211, v42, v43
	s_nop 1
	v_permlane16_swap_b32_e32 v208, v210
	v_permlane16_swap_b32_e32 v209, v211
	ds_bpermute_b32 v208, v244, v208
	ds_bpermute_b32 v209, v244, v209
	ds_bpermute_b32 v210, v244, v210
	ds_bpermute_b32 v211, v244, v211
	s_waitcnt lgkmcnt(4)
	global_store_dwordx4 v67, v[204:207], s[38:39] offset:256
	v_add_u32_e32 v67, 0x10000, v67
	s_waitcnt vmcnt(17)
	v_lshlrev_b32_e32 v232, 16, v212
	v_and_b32_e32 v233, s30, v212
	v_lshlrev_b32_e32 v234, 16, v213
	v_and_b32_e32 v235, s30, v213
	v_max_f32_e32 v232, s31, v232
	v_max_f32_e32 v233, s31, v233
	v_max_f32_e32 v234, s31, v234
	v_max_f32_e32 v235, s31, v235
	v_pk_mul_f32 v[12:13], v[12:13], v[232:233]
	v_pk_mul_f32 v[14:15], v[14:15], v[234:235]
	v_cvt_pk_bf16_f32 v212, v12, v13
	v_cvt_pk_bf16_f32 v213, v14, v15
	s_waitcnt vmcnt(16)
	v_lshlrev_b32_e32 v232, 16, v214
	v_and_b32_e32 v233, s30, v214
	v_lshlrev_b32_e32 v234, 16, v215
	v_and_b32_e32 v235, s30, v215
	v_max_f32_e32 v232, s31, v232
	v_max_f32_e32 v233, s31, v233
	v_max_f32_e32 v234, s31, v234
	v_max_f32_e32 v235, s31, v235
	v_pk_mul_f32 v[8:9], v[8:9], v[232:233]
	v_pk_mul_f32 v[10:11], v[10:11], v[234:235]
	v_cvt_pk_bf16_f32 v214, v8, v9
	v_cvt_pk_bf16_f32 v215, v10, v11
	s_nop 1
	v_permlane16_swap_b32_e32 v212, v214
	v_permlane16_swap_b32_e32 v213, v215
	ds_bpermute_b32 v212, v244, v212
	ds_bpermute_b32 v213, v244, v213
	ds_bpermute_b32 v214, v244, v214
	ds_bpermute_b32 v215, v244, v215
	s_waitcnt lgkmcnt(4)
	global_store_dwordx4 v67, v[208:211], s[38:39] offset:0
	s_waitcnt vmcnt(16)
	v_lshlrev_b32_e32 v232, 16, v216
	v_and_b32_e32 v233, s30, v216
	v_lshlrev_b32_e32 v234, 16, v217
	v_and_b32_e32 v235, s30, v217
	v_max_f32_e32 v232, s31, v232
	v_max_f32_e32 v233, s31, v233
	v_max_f32_e32 v234, s31, v234
	v_max_f32_e32 v235, s31, v235
	v_pk_mul_f32 v[36:37], v[36:37], v[232:233]
	v_pk_mul_f32 v[38:39], v[38:39], v[234:235]
	v_cvt_pk_bf16_f32 v216, v36, v37
	v_cvt_pk_bf16_f32 v217, v38, v39
	s_waitcnt vmcnt(15)
	v_lshlrev_b32_e32 v232, 16, v218
	v_and_b32_e32 v233, s30, v218
	v_lshlrev_b32_e32 v234, 16, v219
	v_and_b32_e32 v235, s30, v219
	v_max_f32_e32 v232, s31, v232
	v_max_f32_e32 v233, s31, v233
	v_max_f32_e32 v234, s31, v234
	v_max_f32_e32 v235, s31, v235
	v_pk_mul_f32 v[32:33], v[32:33], v[232:233]
	v_pk_mul_f32 v[34:35], v[34:35], v[234:235]
	v_cvt_pk_bf16_f32 v218, v32, v33
	v_cvt_pk_bf16_f32 v219, v34, v35
	s_nop 1
	v_permlane16_swap_b32_e32 v216, v218
	v_permlane16_swap_b32_e32 v217, v219
	ds_bpermute_b32 v216, v244, v216
	ds_bpermute_b32 v217, v244, v217
	ds_bpermute_b32 v218, v244, v218
	ds_bpermute_b32 v219, v244, v219
	s_waitcnt lgkmcnt(4)
	global_store_dwordx4 v67, v[212:215], s[38:39] offset:256
	v_add_u32_e32 v67, 0x10000, v67
	s_waitcnt vmcnt(15)
	v_lshlrev_b32_e32 v232, 16, v220
	v_and_b32_e32 v233, s30, v220
	v_lshlrev_b32_e32 v234, 16, v221
	v_and_b32_e32 v235, s30, v221
	v_max_f32_e32 v232, s31, v232
	v_max_f32_e32 v233, s31, v233
	v_max_f32_e32 v234, s31, v234
	v_max_f32_e32 v235, s31, v235
	v_pk_mul_f32 v[4:5], v[4:5], v[232:233]
	v_pk_mul_f32 v[6:7], v[6:7], v[234:235]
	v_cvt_pk_bf16_f32 v220, v4, v5
	v_cvt_pk_bf16_f32 v221, v6, v7
	s_waitcnt vmcnt(14)
	v_lshlrev_b32_e32 v232, 16, v222
	v_and_b32_e32 v233, s30, v222
	v_lshlrev_b32_e32 v234, 16, v223
	v_and_b32_e32 v235, s30, v223
	v_max_f32_e32 v232, s31, v232
	v_max_f32_e32 v233, s31, v233
	v_max_f32_e32 v234, s31, v234
	v_max_f32_e32 v235, s31, v235
	v_pk_mul_f32 v[0:1], v[0:1], v[232:233]
	v_pk_mul_f32 v[2:3], v[2:3], v[234:235]
	v_cvt_pk_bf16_f32 v222, v0, v1
	v_cvt_pk_bf16_f32 v223, v2, v3
	s_nop 1
	v_permlane16_swap_b32_e32 v220, v222
	v_permlane16_swap_b32_e32 v221, v223
	ds_bpermute_b32 v220, v244, v220
	ds_bpermute_b32 v221, v244, v221
	ds_bpermute_b32 v222, v244, v222
	ds_bpermute_b32 v223, v244, v223
	s_waitcnt lgkmcnt(4)
	global_store_dwordx4 v67, v[216:219], s[38:39] offset:0
	s_waitcnt lgkmcnt(0)
	global_store_dwordx4 v67, v[220:223], s[38:39] offset:256
	s_branch .LBB0_987
